# compress k-loop prefetch depth 4 (three steps of loads in flight)
# speedup vs baseline: 1.0071x; 1.0017x over previous
.LBB0_501:
	v_lshl_add_u32 v92, v45, 6, v46
	v_add_u32_e32 v93, v47, v45
	s_andn2_b64 s[38:39], exec, vcc
	v_add_u32_e32 v64, 0, v92
	v_lshlrev_b32_e32 v183, 2, v64
	v_lshlrev_b32_e32 v64, 8, v64
	v_lshl_add_u64 v[180:181], v[64:65], 0, v[36:37]
	v_mov_b32_e32 v96, 0
	v_mov_b32_e32 v97, 0
	v_mov_b32_e32 v98, 0
	v_mov_b32_e32 v99, 0
	v_add_u32_e32 v182, 0, v93
	v_cmp_gt_i32_e64 s[40:41], s80, v182
	v_add_u32_e32 v182, s44, v182
	v_mul_u32_u24_e32 v182, s66, v182
	v_add_u32_e32 v64, 0, v46
	v_lshl_add_u32 v182, v64, 1, v182
	s_and_b64 s[40:41], s[40:41], s[38:39]
	s_mov_b64 s[4:5], exec
	s_mov_b64 exec, s[40:41]
	global_load_dwordx4 v[96:99], v182, s[34:35]
	s_mov_b64 exec, s[0:1]
	global_load_dwordx4 v[100:103], v183, s[30:31]
	global_load_dwordx4 v[104:107], v183, s[30:31] offset:16
	s_mov_b64 exec, s[4:5]
	global_load_dword v108, v[180:181], off
	global_load_dword v109, v[180:181], off offset:256
	global_load_dword v110, v[180:181], off offset:512
	global_load_dword v111, v[180:181], off offset:768
	global_load_dword v112, v[180:181], off offset:1024
	global_load_dword v113, v[180:181], off offset:1280
	global_load_dword v114, v[180:181], off offset:1536
	global_load_dword v115, v[180:181], off offset:1792
	global_load_dword v116, v[180:181], off offset:128
	global_load_dword v117, v[180:181], off offset:384
	global_load_dword v118, v[180:181], off offset:640
	global_load_dword v119, v[180:181], off offset:896
	global_load_dword v120, v[180:181], off offset:1152
	global_load_dword v121, v[180:181], off offset:1408
	global_load_dword v122, v[180:181], off offset:1664
	global_load_dword v123, v[180:181], off offset:1920
	v_add_u32_e32 v64, 16, v92
	v_lshlrev_b32_e32 v183, 2, v64
	v_lshlrev_b32_e32 v64, 8, v64
	v_lshl_add_u64 v[180:181], v[64:65], 0, v[36:37]
	v_mov_b32_e32 v124, 0
	v_mov_b32_e32 v125, 0
	v_mov_b32_e32 v126, 0
	v_mov_b32_e32 v127, 0
	v_add_u32_e32 v182, 0, v93
	v_cmp_gt_i32_e64 s[40:41], s80, v182
	v_add_u32_e32 v182, s44, v182
	v_mul_u32_u24_e32 v182, s66, v182
	v_add_u32_e32 v64, 16, v46
	v_lshl_add_u32 v182, v64, 1, v182
	s_and_b64 s[40:41], s[40:41], s[38:39]
	s_mov_b64 s[4:5], exec
	s_mov_b64 exec, s[40:41]
	global_load_dwordx4 v[124:127], v182, s[34:35]
	s_mov_b64 exec, s[0:1]
	global_load_dwordx4 v[128:131], v183, s[30:31]
	global_load_dwordx4 v[132:135], v183, s[30:31] offset:16
	s_mov_b64 exec, s[4:5]
	global_load_dword v136, v[180:181], off
	global_load_dword v137, v[180:181], off offset:256
	global_load_dword v138, v[180:181], off offset:512
	global_load_dword v139, v[180:181], off offset:768
	global_load_dword v140, v[180:181], off offset:1024
	global_load_dword v141, v[180:181], off offset:1280
	global_load_dword v142, v[180:181], off offset:1536
	global_load_dword v143, v[180:181], off offset:1792
	global_load_dword v150, v[180:181], off offset:128
	global_load_dword v151, v[180:181], off offset:384
	global_load_dword v152, v[180:181], off offset:640
	global_load_dword v153, v[180:181], off offset:896
	global_load_dword v154, v[180:181], off offset:1152
	global_load_dword v155, v[180:181], off offset:1408
	global_load_dword v156, v[180:181], off offset:1664
	global_load_dword v157, v[180:181], off offset:1920
	v_add_u32_e32 v64, 32, v92
	v_lshlrev_b32_e32 v183, 2, v64
	v_lshlrev_b32_e32 v64, 8, v64
	v_lshl_add_u64 v[180:181], v[64:65], 0, v[36:37]
	v_mov_b32_e32 v200, 0
	v_mov_b32_e32 v201, 0
	v_mov_b32_e32 v202, 0
	v_mov_b32_e32 v203, 0
	v_add_u32_e32 v182, 0, v93
	v_cmp_gt_i32_e64 s[40:41], s80, v182
	v_add_u32_e32 v182, s44, v182
	v_mul_u32_u24_e32 v182, s66, v182
	v_add_u32_e32 v64, 32, v46
	v_lshl_add_u32 v182, v64, 1, v182
	s_and_b64 s[40:41], s[40:41], s[38:39]
	s_mov_b64 s[4:5], exec
	s_mov_b64 exec, s[40:41]
	global_load_dwordx4 v[200:203], v182, s[34:35]
	s_mov_b64 exec, s[0:1]
	global_load_dwordx4 v[204:207], v183, s[30:31]
	global_load_dwordx4 v[208:211], v183, s[30:31] offset:16
	s_mov_b64 exec, s[4:5]
	global_load_dword v212, v[180:181], off
	global_load_dword v213, v[180:181], off offset:256
	global_load_dword v214, v[180:181], off offset:512
	global_load_dword v215, v[180:181], off offset:768
	global_load_dword v216, v[180:181], off offset:1024
	global_load_dword v217, v[180:181], off offset:1280
	global_load_dword v218, v[180:181], off offset:1536
	global_load_dword v219, v[180:181], off offset:1792
	global_load_dword v220, v[180:181], off offset:128
	global_load_dword v221, v[180:181], off offset:384
	global_load_dword v222, v[180:181], off offset:640
	global_load_dword v223, v[180:181], off offset:896
	global_load_dword v224, v[180:181], off offset:1152
	global_load_dword v225, v[180:181], off offset:1408
	global_load_dword v226, v[180:181], off offset:1664
	global_load_dword v227, v[180:181], off offset:1920
	v_add_u32_e32 v64, 48, v92
	v_lshlrev_b32_e32 v183, 2, v64
	v_lshlrev_b32_e32 v64, 8, v64
	v_lshl_add_u64 v[180:181], v[64:65], 0, v[36:37]
	v_mov_b32_e32 v228, 0
	v_mov_b32_e32 v229, 0
	v_mov_b32_e32 v230, 0
	v_mov_b32_e32 v231, 0
	v_add_u32_e32 v182, 0, v93
	v_cmp_gt_i32_e64 s[40:41], s80, v182
	v_add_u32_e32 v182, s44, v182
	v_mul_u32_u24_e32 v182, s66, v182
	v_add_u32_e32 v64, 48, v46
	v_lshl_add_u32 v182, v64, 1, v182
	s_and_b64 s[40:41], s[40:41], s[38:39]
	s_mov_b64 s[4:5], exec
	s_mov_b64 exec, s[40:41]
	global_load_dwordx4 v[228:231], v182, s[34:35]
	s_mov_b64 exec, s[0:1]
	global_load_dwordx4 v[232:235], v183, s[30:31]
	global_load_dwordx4 v[236:239], v183, s[30:31] offset:16
	s_mov_b64 exec, s[4:5]
	global_load_dword v240, v[180:181], off
	global_load_dword v241, v[180:181], off offset:256
	global_load_dword v242, v[180:181], off offset:512
	global_load_dword v243, v[180:181], off offset:768
	global_load_dword v244, v[180:181], off offset:1024
	global_load_dword v245, v[180:181], off offset:1280
	global_load_dword v246, v[180:181], off offset:1536
	global_load_dword v247, v[180:181], off offset:1792
	global_load_dword v248, v[180:181], off offset:128
	global_load_dword v249, v[180:181], off offset:384
	global_load_dword v250, v[180:181], off offset:640
	global_load_dword v251, v[180:181], off offset:896
	global_load_dword v66, v[180:181], off offset:1152
	global_load_dword v67, v[180:181], off offset:1408
	global_load_dword v68, v[180:181], off offset:1664
	global_load_dword v69, v[180:181], off offset:1920
	s_waitcnt vmcnt(57)
	s_mov_b64 s[4:5], exec
	s_mov_b64 exec, s[0:1]
	v_cvt_pk_bf16_f32 v96, v100, v101
	v_cvt_pk_bf16_f32 v97, v102, v103
	v_cvt_pk_bf16_f32 v98, v104, v105
	v_cvt_pk_bf16_f32 v99, v106, v107
	s_mov_b64 exec, s[4:5]
	v_cvt_pk_bf16_f32 v158, v108, v109
	v_cvt_pk_bf16_f32 v159, v110, v111
	v_cvt_pk_bf16_f32 v160, v112, v113
	v_cvt_pk_bf16_f32 v161, v114, v115
	v_cvt_pk_bf16_f32 v176, v116, v117
	v_cvt_pk_bf16_f32 v177, v118, v119
	v_cvt_pk_bf16_f32 v178, v120, v121
	v_cvt_pk_bf16_f32 v179, v122, v123
	s_nop 1
	v_mfma_f32_32x32x16_bf16 v[16:31], v[96:99], v[158:161], v[16:31]
	v_mfma_f32_32x32x16_bf16 v[0:15], v[96:99], v[176:179], v[0:15]
	v_add_u32_e32 v64, 64, v92
	v_lshlrev_b32_e32 v183, 2, v64
	v_lshlrev_b32_e32 v64, 8, v64
	v_lshl_add_u64 v[180:181], v[64:65], 0, v[36:37]
	v_mov_b32_e32 v96, 0
	v_mov_b32_e32 v97, 0
	v_mov_b32_e32 v98, 0
	v_mov_b32_e32 v99, 0
	v_add_u32_e32 v182, 1, v93
	v_cmp_gt_i32_e64 s[40:41], s80, v182
	v_add_u32_e32 v182, s44, v182
	v_mul_u32_u24_e32 v182, s66, v182
	v_add_u32_e32 v64, 0, v46
	v_lshl_add_u32 v182, v64, 1, v182
	s_and_b64 s[40:41], s[40:41], s[38:39]
	s_mov_b64 s[4:5], exec
	s_mov_b64 exec, s[40:41]
	global_load_dwordx4 v[96:99], v182, s[34:35]
	s_mov_b64 exec, s[0:1]
	global_load_dwordx4 v[100:103], v183, s[30:31]
	global_load_dwordx4 v[104:107], v183, s[30:31] offset:16
	s_mov_b64 exec, s[4:5]
	global_load_dword v108, v[180:181], off
	global_load_dword v109, v[180:181], off offset:256
	global_load_dword v110, v[180:181], off offset:512
	global_load_dword v111, v[180:181], off offset:768
	global_load_dword v112, v[180:181], off offset:1024
	global_load_dword v113, v[180:181], off offset:1280
	global_load_dword v114, v[180:181], off offset:1536
	global_load_dword v115, v[180:181], off offset:1792
	global_load_dword v116, v[180:181], off offset:128
	global_load_dword v117, v[180:181], off offset:384
	global_load_dword v118, v[180:181], off offset:640
	global_load_dword v119, v[180:181], off offset:896
	global_load_dword v120, v[180:181], off offset:1152
	global_load_dword v121, v[180:181], off offset:1408
	global_load_dword v122, v[180:181], off offset:1664
	global_load_dword v123, v[180:181], off offset:1920
	s_waitcnt vmcnt(57)
	s_mov_b64 s[4:5], exec
	s_mov_b64 exec, s[0:1]
	v_cvt_pk_bf16_f32 v124, v128, v129
	v_cvt_pk_bf16_f32 v125, v130, v131
	v_cvt_pk_bf16_f32 v126, v132, v133
	v_cvt_pk_bf16_f32 v127, v134, v135
	s_mov_b64 exec, s[4:5]
	v_cvt_pk_bf16_f32 v158, v136, v137
	v_cvt_pk_bf16_f32 v159, v138, v139
	v_cvt_pk_bf16_f32 v160, v140, v141
	v_cvt_pk_bf16_f32 v161, v142, v143
	v_cvt_pk_bf16_f32 v176, v150, v151
	v_cvt_pk_bf16_f32 v177, v152, v153
	v_cvt_pk_bf16_f32 v178, v154, v155
	v_cvt_pk_bf16_f32 v179, v156, v157
	s_nop 1
	v_mfma_f32_32x32x16_bf16 v[16:31], v[124:127], v[158:161], v[16:31]
	v_mfma_f32_32x32x16_bf16 v[0:15], v[124:127], v[176:179], v[0:15]
	v_add_u32_e32 v64, 80, v92
	v_lshlrev_b32_e32 v183, 2, v64
	v_lshlrev_b32_e32 v64, 8, v64
	v_lshl_add_u64 v[180:181], v[64:65], 0, v[36:37]
	v_mov_b32_e32 v124, 0
	v_mov_b32_e32 v125, 0
	v_mov_b32_e32 v126, 0
	v_mov_b32_e32 v127, 0
	v_add_u32_e32 v182, 1, v93
	v_cmp_gt_i32_e64 s[40:41], s80, v182
	v_add_u32_e32 v182, s44, v182
	v_mul_u32_u24_e32 v182, s66, v182
	v_add_u32_e32 v64, 16, v46
	v_lshl_add_u32 v182, v64, 1, v182
	s_and_b64 s[40:41], s[40:41], s[38:39]
	s_mov_b64 s[4:5], exec
	s_mov_b64 exec, s[40:41]
	global_load_dwordx4 v[124:127], v182, s[34:35]
	s_mov_b64 exec, s[0:1]
	global_load_dwordx4 v[128:131], v183, s[30:31]
	global_load_dwordx4 v[132:135], v183, s[30:31] offset:16
	s_mov_b64 exec, s[4:5]
	global_load_dword v136, v[180:181], off
	global_load_dword v137, v[180:181], off offset:256
	global_load_dword v138, v[180:181], off offset:512
	global_load_dword v139, v[180:181], off offset:768
	global_load_dword v140, v[180:181], off offset:1024
	global_load_dword v141, v[180:181], off offset:1280
	global_load_dword v142, v[180:181], off offset:1536
	global_load_dword v143, v[180:181], off offset:1792
	global_load_dword v150, v[180:181], off offset:128
	global_load_dword v151, v[180:181], off offset:384
	global_load_dword v152, v[180:181], off offset:640
	global_load_dword v153, v[180:181], off offset:896
	global_load_dword v154, v[180:181], off offset:1152
	global_load_dword v155, v[180:181], off offset:1408
	global_load_dword v156, v[180:181], off offset:1664
	global_load_dword v157, v[180:181], off offset:1920
	s_waitcnt vmcnt(57)
	s_mov_b64 s[4:5], exec
	s_mov_b64 exec, s[0:1]
	v_cvt_pk_bf16_f32 v200, v204, v205
	v_cvt_pk_bf16_f32 v201, v206, v207
	v_cvt_pk_bf16_f32 v202, v208, v209
	v_cvt_pk_bf16_f32 v203, v210, v211
	s_mov_b64 exec, s[4:5]
	v_cvt_pk_bf16_f32 v158, v212, v213
	v_cvt_pk_bf16_f32 v159, v214, v215
	v_cvt_pk_bf16_f32 v160, v216, v217
	v_cvt_pk_bf16_f32 v161, v218, v219
	v_cvt_pk_bf16_f32 v176, v220, v221
	v_cvt_pk_bf16_f32 v177, v222, v223
	v_cvt_pk_bf16_f32 v178, v224, v225
	v_cvt_pk_bf16_f32 v179, v226, v227
	s_nop 1
	v_mfma_f32_32x32x16_bf16 v[16:31], v[200:203], v[158:161], v[16:31]
	v_mfma_f32_32x32x16_bf16 v[0:15], v[200:203], v[176:179], v[0:15]
	v_add_u32_e32 v64, 96, v92
	v_lshlrev_b32_e32 v183, 2, v64
	v_lshlrev_b32_e32 v64, 8, v64
	v_lshl_add_u64 v[180:181], v[64:65], 0, v[36:37]
	v_mov_b32_e32 v200, 0
	v_mov_b32_e32 v201, 0
	v_mov_b32_e32 v202, 0
	v_mov_b32_e32 v203, 0
	v_add_u32_e32 v182, 1, v93
	v_cmp_gt_i32_e64 s[40:41], s80, v182
	v_add_u32_e32 v182, s44, v182
	v_mul_u32_u24_e32 v182, s66, v182
	v_add_u32_e32 v64, 32, v46
	v_lshl_add_u32 v182, v64, 1, v182
	s_and_b64 s[40:41], s[40:41], s[38:39]
	s_mov_b64 s[4:5], exec
	s_mov_b64 exec, s[40:41]
	global_load_dwordx4 v[200:203], v182, s[34:35]
	s_mov_b64 exec, s[0:1]
	global_load_dwordx4 v[204:207], v183, s[30:31]
	global_load_dwordx4 v[208:211], v183, s[30:31] offset:16
	s_mov_b64 exec, s[4:5]
	global_load_dword v212, v[180:181], off
	global_load_dword v213, v[180:181], off offset:256
	global_load_dword v214, v[180:181], off offset:512
	global_load_dword v215, v[180:181], off offset:768
	global_load_dword v216, v[180:181], off offset:1024
	global_load_dword v217, v[180:181], off offset:1280
	global_load_dword v218, v[180:181], off offset:1536
	global_load_dword v219, v[180:181], off offset:1792
	global_load_dword v220, v[180:181], off offset:128
	global_load_dword v221, v[180:181], off offset:384
	global_load_dword v222, v[180:181], off offset:640
	global_load_dword v223, v[180:181], off offset:896
	global_load_dword v224, v[180:181], off offset:1152
	global_load_dword v225, v[180:181], off offset:1408
	global_load_dword v226, v[180:181], off offset:1664
	global_load_dword v227, v[180:181], off offset:1920
	s_waitcnt vmcnt(57)
	s_mov_b64 s[4:5], exec
	s_mov_b64 exec, s[0:1]
	v_cvt_pk_bf16_f32 v228, v232, v233
	v_cvt_pk_bf16_f32 v229, v234, v235
	v_cvt_pk_bf16_f32 v230, v236, v237
	v_cvt_pk_bf16_f32 v231, v238, v239
	s_mov_b64 exec, s[4:5]
	v_cvt_pk_bf16_f32 v158, v240, v241
	v_cvt_pk_bf16_f32 v159, v242, v243
	v_cvt_pk_bf16_f32 v160, v244, v245
	v_cvt_pk_bf16_f32 v161, v246, v247
	v_cvt_pk_bf16_f32 v176, v248, v249
	v_cvt_pk_bf16_f32 v177, v250, v251
	v_cvt_pk_bf16_f32 v178, v66, v67
	v_cvt_pk_bf16_f32 v179, v68, v69
	s_nop 1
	v_mfma_f32_32x32x16_bf16 v[16:31], v[228:231], v[158:161], v[16:31]
	v_mfma_f32_32x32x16_bf16 v[0:15], v[228:231], v[176:179], v[0:15]
	v_add_u32_e32 v64, 112, v92
	v_lshlrev_b32_e32 v183, 2, v64
	v_lshlrev_b32_e32 v64, 8, v64
	v_lshl_add_u64 v[180:181], v[64:65], 0, v[36:37]
	v_mov_b32_e32 v228, 0
	v_mov_b32_e32 v229, 0
	v_mov_b32_e32 v230, 0
	v_mov_b32_e32 v231, 0
	v_add_u32_e32 v182, 1, v93
	v_cmp_gt_i32_e64 s[40:41], s80, v182
	v_add_u32_e32 v182, s44, v182
	v_mul_u32_u24_e32 v182, s66, v182
	v_add_u32_e32 v64, 48, v46
	v_lshl_add_u32 v182, v64, 1, v182
	s_and_b64 s[40:41], s[40:41], s[38:39]
	s_mov_b64 s[4:5], exec
	s_mov_b64 exec, s[40:41]
	global_load_dwordx4 v[228:231], v182, s[34:35]
	s_mov_b64 exec, s[0:1]
	global_load_dwordx4 v[232:235], v183, s[30:31]
	global_load_dwordx4 v[236:239], v183, s[30:31] offset:16
	s_mov_b64 exec, s[4:5]
	global_load_dword v240, v[180:181], off
	global_load_dword v241, v[180:181], off offset:256
	global_load_dword v242, v[180:181], off offset:512
	global_load_dword v243, v[180:181], off offset:768
	global_load_dword v244, v[180:181], off offset:1024
	global_load_dword v245, v[180:181], off offset:1280
	global_load_dword v246, v[180:181], off offset:1536
	global_load_dword v247, v[180:181], off offset:1792
	global_load_dword v248, v[180:181], off offset:128
	global_load_dword v249, v[180:181], off offset:384
	global_load_dword v250, v[180:181], off offset:640
	global_load_dword v251, v[180:181], off offset:896
	global_load_dword v66, v[180:181], off offset:1152
	global_load_dword v67, v[180:181], off offset:1408
	global_load_dword v68, v[180:181], off offset:1664
	global_load_dword v69, v[180:181], off offset:1920
	s_waitcnt vmcnt(57)
	s_mov_b64 s[4:5], exec
	s_mov_b64 exec, s[0:1]
	v_cvt_pk_bf16_f32 v96, v100, v101
	v_cvt_pk_bf16_f32 v97, v102, v103
	v_cvt_pk_bf16_f32 v98, v104, v105
	v_cvt_pk_bf16_f32 v99, v106, v107
	s_mov_b64 exec, s[4:5]
	v_cvt_pk_bf16_f32 v158, v108, v109
	v_cvt_pk_bf16_f32 v159, v110, v111
	v_cvt_pk_bf16_f32 v160, v112, v113
	v_cvt_pk_bf16_f32 v161, v114, v115
	v_cvt_pk_bf16_f32 v176, v116, v117
	v_cvt_pk_bf16_f32 v177, v118, v119
	v_cvt_pk_bf16_f32 v178, v120, v121
	v_cvt_pk_bf16_f32 v179, v122, v123
	s_nop 1
	v_mfma_f32_32x32x16_bf16 v[16:31], v[96:99], v[158:161], v[16:31]
	v_mfma_f32_32x32x16_bf16 v[0:15], v[96:99], v[176:179], v[0:15]
	v_add_u32_e32 v64, 128, v92
	v_lshlrev_b32_e32 v183, 2, v64
	v_lshlrev_b32_e32 v64, 8, v64
	v_lshl_add_u64 v[180:181], v[64:65], 0, v[36:37]
	v_mov_b32_e32 v96, 0
	v_mov_b32_e32 v97, 0
	v_mov_b32_e32 v98, 0
	v_mov_b32_e32 v99, 0
	v_add_u32_e32 v182, 2, v93
	v_cmp_gt_i32_e64 s[40:41], s80, v182
	v_add_u32_e32 v182, s44, v182
	v_mul_u32_u24_e32 v182, s66, v182
	v_add_u32_e32 v64, 0, v46
	v_lshl_add_u32 v182, v64, 1, v182
	s_and_b64 s[40:41], s[40:41], s[38:39]
	s_mov_b64 s[4:5], exec
	s_mov_b64 exec, s[40:41]
	global_load_dwordx4 v[96:99], v182, s[34:35]
	s_mov_b64 exec, s[0:1]
	global_load_dwordx4 v[100:103], v183, s[30:31]
	global_load_dwordx4 v[104:107], v183, s[30:31] offset:16
	s_mov_b64 exec, s[4:5]
	global_load_dword v108, v[180:181], off
	global_load_dword v109, v[180:181], off offset:256
	global_load_dword v110, v[180:181], off offset:512
	global_load_dword v111, v[180:181], off offset:768
	global_load_dword v112, v[180:181], off offset:1024
	global_load_dword v113, v[180:181], off offset:1280
	global_load_dword v114, v[180:181], off offset:1536
	global_load_dword v115, v[180:181], off offset:1792
	global_load_dword v116, v[180:181], off offset:128
	global_load_dword v117, v[180:181], off offset:384
	global_load_dword v118, v[180:181], off offset:640
	global_load_dword v119, v[180:181], off offset:896
	global_load_dword v120, v[180:181], off offset:1152
	global_load_dword v121, v[180:181], off offset:1408
	global_load_dword v122, v[180:181], off offset:1664
	global_load_dword v123, v[180:181], off offset:1920
	s_waitcnt vmcnt(57)
	s_mov_b64 s[4:5], exec
	s_mov_b64 exec, s[0:1]
	v_cvt_pk_bf16_f32 v124, v128, v129
	v_cvt_pk_bf16_f32 v125, v130, v131
	v_cvt_pk_bf16_f32 v126, v132, v133
	v_cvt_pk_bf16_f32 v127, v134, v135
	s_mov_b64 exec, s[4:5]
	v_cvt_pk_bf16_f32 v158, v136, v137
	v_cvt_pk_bf16_f32 v159, v138, v139
	v_cvt_pk_bf16_f32 v160, v140, v141
	v_cvt_pk_bf16_f32 v161, v142, v143
	v_cvt_pk_bf16_f32 v176, v150, v151
	v_cvt_pk_bf16_f32 v177, v152, v153
	v_cvt_pk_bf16_f32 v178, v154, v155
	v_cvt_pk_bf16_f32 v179, v156, v157
	s_nop 1
	v_mfma_f32_32x32x16_bf16 v[16:31], v[124:127], v[158:161], v[16:31]
	v_mfma_f32_32x32x16_bf16 v[0:15], v[124:127], v[176:179], v[0:15]
	v_add_u32_e32 v64, 144, v92
	v_lshlrev_b32_e32 v183, 2, v64
	v_lshlrev_b32_e32 v64, 8, v64
	v_lshl_add_u64 v[180:181], v[64:65], 0, v[36:37]
	v_mov_b32_e32 v124, 0
	v_mov_b32_e32 v125, 0
	v_mov_b32_e32 v126, 0
	v_mov_b32_e32 v127, 0
	v_add_u32_e32 v182, 2, v93
	v_cmp_gt_i32_e64 s[40:41], s80, v182
	v_add_u32_e32 v182, s44, v182
	v_mul_u32_u24_e32 v182, s66, v182
	v_add_u32_e32 v64, 16, v46
	v_lshl_add_u32 v182, v64, 1, v182
	s_and_b64 s[40:41], s[40:41], s[38:39]
	s_mov_b64 s[4:5], exec
	s_mov_b64 exec, s[40:41]
	global_load_dwordx4 v[124:127], v182, s[34:35]
	s_mov_b64 exec, s[0:1]
	global_load_dwordx4 v[128:131], v183, s[30:31]
	global_load_dwordx4 v[132:135], v183, s[30:31] offset:16
	s_mov_b64 exec, s[4:5]
	global_load_dword v136, v[180:181], off
	global_load_dword v137, v[180:181], off offset:256
	global_load_dword v138, v[180:181], off offset:512
	global_load_dword v139, v[180:181], off offset:768
	global_load_dword v140, v[180:181], off offset:1024
	global_load_dword v141, v[180:181], off offset:1280
	global_load_dword v142, v[180:181], off offset:1536
	global_load_dword v143, v[180:181], off offset:1792
	global_load_dword v150, v[180:181], off offset:128
	global_load_dword v151, v[180:181], off offset:384
	global_load_dword v152, v[180:181], off offset:640
	global_load_dword v153, v[180:181], off offset:896
	global_load_dword v154, v[180:181], off offset:1152
	global_load_dword v155, v[180:181], off offset:1408
	global_load_dword v156, v[180:181], off offset:1664
	global_load_dword v157, v[180:181], off offset:1920
	s_waitcnt vmcnt(57)
	s_mov_b64 s[4:5], exec
	s_mov_b64 exec, s[0:1]
	v_cvt_pk_bf16_f32 v200, v204, v205
	v_cvt_pk_bf16_f32 v201, v206, v207
	v_cvt_pk_bf16_f32 v202, v208, v209
	v_cvt_pk_bf16_f32 v203, v210, v211
	s_mov_b64 exec, s[4:5]
	v_cvt_pk_bf16_f32 v158, v212, v213
	v_cvt_pk_bf16_f32 v159, v214, v215
	v_cvt_pk_bf16_f32 v160, v216, v217
	v_cvt_pk_bf16_f32 v161, v218, v219
	v_cvt_pk_bf16_f32 v176, v220, v221
	v_cvt_pk_bf16_f32 v177, v222, v223
	v_cvt_pk_bf16_f32 v178, v224, v225
	v_cvt_pk_bf16_f32 v179, v226, v227
	s_nop 1
	v_mfma_f32_32x32x16_bf16 v[16:31], v[200:203], v[158:161], v[16:31]
	v_mfma_f32_32x32x16_bf16 v[0:15], v[200:203], v[176:179], v[0:15]
	v_add_u32_e32 v64, 160, v92
	v_lshlrev_b32_e32 v183, 2, v64
	v_lshlrev_b32_e32 v64, 8, v64
	v_lshl_add_u64 v[180:181], v[64:65], 0, v[36:37]
	v_mov_b32_e32 v200, 0
	v_mov_b32_e32 v201, 0
	v_mov_b32_e32 v202, 0
	v_mov_b32_e32 v203, 0
	v_add_u32_e32 v182, 2, v93
	v_cmp_gt_i32_e64 s[40:41], s80, v182
	v_add_u32_e32 v182, s44, v182
	v_mul_u32_u24_e32 v182, s66, v182
	v_add_u32_e32 v64, 32, v46
	v_lshl_add_u32 v182, v64, 1, v182
	s_and_b64 s[40:41], s[40:41], s[38:39]
	s_mov_b64 s[4:5], exec
	s_mov_b64 exec, s[40:41]
	global_load_dwordx4 v[200:203], v182, s[34:35]
	s_mov_b64 exec, s[0:1]
	global_load_dwordx4 v[204:207], v183, s[30:31]
	global_load_dwordx4 v[208:211], v183, s[30:31] offset:16
	s_mov_b64 exec, s[4:5]
	global_load_dword v212, v[180:181], off
	global_load_dword v213, v[180:181], off offset:256
	global_load_dword v214, v[180:181], off offset:512
	global_load_dword v215, v[180:181], off offset:768
	global_load_dword v216, v[180:181], off offset:1024
	global_load_dword v217, v[180:181], off offset:1280
	global_load_dword v218, v[180:181], off offset:1536
	global_load_dword v219, v[180:181], off offset:1792
	global_load_dword v220, v[180:181], off offset:128
	global_load_dword v221, v[180:181], off offset:384
	global_load_dword v222, v[180:181], off offset:640
	global_load_dword v223, v[180:181], off offset:896
	global_load_dword v224, v[180:181], off offset:1152
	global_load_dword v225, v[180:181], off offset:1408
	global_load_dword v226, v[180:181], off offset:1664
	global_load_dword v227, v[180:181], off offset:1920
	s_waitcnt vmcnt(57)
	s_mov_b64 s[4:5], exec
	s_mov_b64 exec, s[0:1]
	v_cvt_pk_bf16_f32 v228, v232, v233
	v_cvt_pk_bf16_f32 v229, v234, v235
	v_cvt_pk_bf16_f32 v230, v236, v237
	v_cvt_pk_bf16_f32 v231, v238, v239
	s_mov_b64 exec, s[4:5]
	v_cvt_pk_bf16_f32 v158, v240, v241
	v_cvt_pk_bf16_f32 v159, v242, v243
	v_cvt_pk_bf16_f32 v160, v244, v245
	v_cvt_pk_bf16_f32 v161, v246, v247
	v_cvt_pk_bf16_f32 v176, v248, v249
	v_cvt_pk_bf16_f32 v177, v250, v251
	v_cvt_pk_bf16_f32 v178, v66, v67
	v_cvt_pk_bf16_f32 v179, v68, v69
	s_nop 1
	v_mfma_f32_32x32x16_bf16 v[16:31], v[228:231], v[158:161], v[16:31]
	v_mfma_f32_32x32x16_bf16 v[0:15], v[228:231], v[176:179], v[0:15]
	v_add_u32_e32 v64, 176, v92
	v_lshlrev_b32_e32 v183, 2, v64
	v_lshlrev_b32_e32 v64, 8, v64
	v_lshl_add_u64 v[180:181], v[64:65], 0, v[36:37]
	v_mov_b32_e32 v228, 0
	v_mov_b32_e32 v229, 0
	v_mov_b32_e32 v230, 0
	v_mov_b32_e32 v231, 0
	v_add_u32_e32 v182, 2, v93
	v_cmp_gt_i32_e64 s[40:41], s80, v182
	v_add_u32_e32 v182, s44, v182
	v_mul_u32_u24_e32 v182, s66, v182
	v_add_u32_e32 v64, 48, v46
	v_lshl_add_u32 v182, v64, 1, v182
	s_and_b64 s[40:41], s[40:41], s[38:39]
	s_mov_b64 s[4:5], exec
	s_mov_b64 exec, s[40:41]
	global_load_dwordx4 v[228:231], v182, s[34:35]
	s_mov_b64 exec, s[0:1]
	global_load_dwordx4 v[232:235], v183, s[30:31]
	global_load_dwordx4 v[236:239], v183, s[30:31] offset:16
	s_mov_b64 exec, s[4:5]
	global_load_dword v240, v[180:181], off
	global_load_dword v241, v[180:181], off offset:256
	global_load_dword v242, v[180:181], off offset:512
	global_load_dword v243, v[180:181], off offset:768
	global_load_dword v244, v[180:181], off offset:1024
	global_load_dword v245, v[180:181], off offset:1280
	global_load_dword v246, v[180:181], off offset:1536
	global_load_dword v247, v[180:181], off offset:1792
	global_load_dword v248, v[180:181], off offset:128
	global_load_dword v249, v[180:181], off offset:384
	global_load_dword v250, v[180:181], off offset:640
	global_load_dword v251, v[180:181], off offset:896
	global_load_dword v66, v[180:181], off offset:1152
	global_load_dword v67, v[180:181], off offset:1408
	global_load_dword v68, v[180:181], off offset:1664
	global_load_dword v69, v[180:181], off offset:1920
	s_waitcnt vmcnt(57)
	s_mov_b64 s[4:5], exec
	s_mov_b64 exec, s[0:1]
	v_cvt_pk_bf16_f32 v96, v100, v101
	v_cvt_pk_bf16_f32 v97, v102, v103
	v_cvt_pk_bf16_f32 v98, v104, v105
	v_cvt_pk_bf16_f32 v99, v106, v107
	s_mov_b64 exec, s[4:5]
	v_cvt_pk_bf16_f32 v158, v108, v109
	v_cvt_pk_bf16_f32 v159, v110, v111
	v_cvt_pk_bf16_f32 v160, v112, v113
	v_cvt_pk_bf16_f32 v161, v114, v115
	v_cvt_pk_bf16_f32 v176, v116, v117
	v_cvt_pk_bf16_f32 v177, v118, v119
	v_cvt_pk_bf16_f32 v178, v120, v121
	v_cvt_pk_bf16_f32 v179, v122, v123
	s_nop 1
	v_mfma_f32_32x32x16_bf16 v[16:31], v[96:99], v[158:161], v[16:31]
	v_mfma_f32_32x32x16_bf16 v[0:15], v[96:99], v[176:179], v[0:15]
	v_add_u32_e32 v64, 192, v92
	v_lshlrev_b32_e32 v183, 2, v64
	v_lshlrev_b32_e32 v64, 8, v64
	v_lshl_add_u64 v[180:181], v[64:65], 0, v[36:37]
	v_mov_b32_e32 v96, 0
	v_mov_b32_e32 v97, 0
	v_mov_b32_e32 v98, 0
	v_mov_b32_e32 v99, 0
	v_add_u32_e32 v182, 3, v93
	v_cmp_gt_i32_e64 s[40:41], s80, v182
	v_add_u32_e32 v182, s44, v182
	v_mul_u32_u24_e32 v182, s66, v182
	v_add_u32_e32 v64, 0, v46
	v_lshl_add_u32 v182, v64, 1, v182
	s_and_b64 s[40:41], s[40:41], s[38:39]
	s_mov_b64 s[4:5], exec
	s_mov_b64 exec, s[40:41]
	global_load_dwordx4 v[96:99], v182, s[34:35]
	s_mov_b64 exec, s[0:1]
	global_load_dwordx4 v[100:103], v183, s[30:31]
	global_load_dwordx4 v[104:107], v183, s[30:31] offset:16
	s_mov_b64 exec, s[4:5]
	global_load_dword v108, v[180:181], off
	global_load_dword v109, v[180:181], off offset:256
	global_load_dword v110, v[180:181], off offset:512
	global_load_dword v111, v[180:181], off offset:768
	global_load_dword v112, v[180:181], off offset:1024
	global_load_dword v113, v[180:181], off offset:1280
	global_load_dword v114, v[180:181], off offset:1536
	global_load_dword v115, v[180:181], off offset:1792
	global_load_dword v116, v[180:181], off offset:128
	global_load_dword v117, v[180:181], off offset:384
	global_load_dword v118, v[180:181], off offset:640
	global_load_dword v119, v[180:181], off offset:896
	global_load_dword v120, v[180:181], off offset:1152
	global_load_dword v121, v[180:181], off offset:1408
	global_load_dword v122, v[180:181], off offset:1664
	global_load_dword v123, v[180:181], off offset:1920
	s_waitcnt vmcnt(57)
	s_mov_b64 s[4:5], exec
	s_mov_b64 exec, s[0:1]
	v_cvt_pk_bf16_f32 v124, v128, v129
	v_cvt_pk_bf16_f32 v125, v130, v131
	v_cvt_pk_bf16_f32 v126, v132, v133
	v_cvt_pk_bf16_f32 v127, v134, v135
	s_mov_b64 exec, s[4:5]
	v_cvt_pk_bf16_f32 v158, v136, v137
	v_cvt_pk_bf16_f32 v159, v138, v139
	v_cvt_pk_bf16_f32 v160, v140, v141
	v_cvt_pk_bf16_f32 v161, v142, v143
	v_cvt_pk_bf16_f32 v176, v150, v151
	v_cvt_pk_bf16_f32 v177, v152, v153
	v_cvt_pk_bf16_f32 v178, v154, v155
	v_cvt_pk_bf16_f32 v179, v156, v157
	s_nop 1
	v_mfma_f32_32x32x16_bf16 v[16:31], v[124:127], v[158:161], v[16:31]
	v_mfma_f32_32x32x16_bf16 v[0:15], v[124:127], v[176:179], v[0:15]
	v_add_u32_e32 v64, 208, v92
	v_lshlrev_b32_e32 v183, 2, v64
	v_lshlrev_b32_e32 v64, 8, v64
	v_lshl_add_u64 v[180:181], v[64:65], 0, v[36:37]
	v_mov_b32_e32 v124, 0
	v_mov_b32_e32 v125, 0
	v_mov_b32_e32 v126, 0
	v_mov_b32_e32 v127, 0
	v_add_u32_e32 v182, 3, v93
	v_cmp_gt_i32_e64 s[40:41], s80, v182
	v_add_u32_e32 v182, s44, v182
	v_mul_u32_u24_e32 v182, s66, v182
	v_add_u32_e32 v64, 16, v46
	v_lshl_add_u32 v182, v64, 1, v182
	s_and_b64 s[40:41], s[40:41], s[38:39]
	s_mov_b64 s[4:5], exec
	s_mov_b64 exec, s[40:41]
	global_load_dwordx4 v[124:127], v182, s[34:35]
	s_mov_b64 exec, s[0:1]
	global_load_dwordx4 v[128:131], v183, s[30:31]
	global_load_dwordx4 v[132:135], v183, s[30:31] offset:16
	s_mov_b64 exec, s[4:5]
	global_load_dword v136, v[180:181], off
	global_load_dword v137, v[180:181], off offset:256
	global_load_dword v138, v[180:181], off offset:512
	global_load_dword v139, v[180:181], off offset:768
	global_load_dword v140, v[180:181], off offset:1024
	global_load_dword v141, v[180:181], off offset:1280
	global_load_dword v142, v[180:181], off offset:1536
	global_load_dword v143, v[180:181], off offset:1792
	global_load_dword v150, v[180:181], off offset:128
	global_load_dword v151, v[180:181], off offset:384
	global_load_dword v152, v[180:181], off offset:640
	global_load_dword v153, v[180:181], off offset:896
	global_load_dword v154, v[180:181], off offset:1152
	global_load_dword v155, v[180:181], off offset:1408
	global_load_dword v156, v[180:181], off offset:1664
	global_load_dword v157, v[180:181], off offset:1920
	s_waitcnt vmcnt(57)
	s_mov_b64 s[4:5], exec
	s_mov_b64 exec, s[0:1]
	v_cvt_pk_bf16_f32 v200, v204, v205
	v_cvt_pk_bf16_f32 v201, v206, v207
	v_cvt_pk_bf16_f32 v202, v208, v209
	v_cvt_pk_bf16_f32 v203, v210, v211
	s_mov_b64 exec, s[4:5]
	v_cvt_pk_bf16_f32 v158, v212, v213
	v_cvt_pk_bf16_f32 v159, v214, v215
	v_cvt_pk_bf16_f32 v160, v216, v217
	v_cvt_pk_bf16_f32 v161, v218, v219
	v_cvt_pk_bf16_f32 v176, v220, v221
	v_cvt_pk_bf16_f32 v177, v222, v223
	v_cvt_pk_bf16_f32 v178, v224, v225
	v_cvt_pk_bf16_f32 v179, v226, v227
	s_nop 1
	v_mfma_f32_32x32x16_bf16 v[16:31], v[200:203], v[158:161], v[16:31]
	v_mfma_f32_32x32x16_bf16 v[0:15], v[200:203], v[176:179], v[0:15]
	v_add_u32_e32 v64, 224, v92
	v_lshlrev_b32_e32 v183, 2, v64
	v_lshlrev_b32_e32 v64, 8, v64
	v_lshl_add_u64 v[180:181], v[64:65], 0, v[36:37]
	v_mov_b32_e32 v200, 0
	v_mov_b32_e32 v201, 0
	v_mov_b32_e32 v202, 0
	v_mov_b32_e32 v203, 0
	v_add_u32_e32 v182, 3, v93
	v_cmp_gt_i32_e64 s[40:41], s80, v182
	v_add_u32_e32 v182, s44, v182
	v_mul_u32_u24_e32 v182, s66, v182
	v_add_u32_e32 v64, 32, v46
	v_lshl_add_u32 v182, v64, 1, v182
	s_and_b64 s[40:41], s[40:41], s[38:39]
	s_mov_b64 s[4:5], exec
	s_mov_b64 exec, s[40:41]
	global_load_dwordx4 v[200:203], v182, s[34:35]
	s_mov_b64 exec, s[0:1]
	global_load_dwordx4 v[204:207], v183, s[30:31]
	global_load_dwordx4 v[208:211], v183, s[30:31] offset:16
	s_mov_b64 exec, s[4:5]
	global_load_dword v212, v[180:181], off
	global_load_dword v213, v[180:181], off offset:256
	global_load_dword v214, v[180:181], off offset:512
	global_load_dword v215, v[180:181], off offset:768
	global_load_dword v216, v[180:181], off offset:1024
	global_load_dword v217, v[180:181], off offset:1280
	global_load_dword v218, v[180:181], off offset:1536
	global_load_dword v219, v[180:181], off offset:1792
	global_load_dword v220, v[180:181], off offset:128
	global_load_dword v221, v[180:181], off offset:384
	global_load_dword v222, v[180:181], off offset:640
	global_load_dword v223, v[180:181], off offset:896
	global_load_dword v224, v[180:181], off offset:1152
	global_load_dword v225, v[180:181], off offset:1408
	global_load_dword v226, v[180:181], off offset:1664
	global_load_dword v227, v[180:181], off offset:1920
	s_waitcnt vmcnt(57)
	s_mov_b64 s[4:5], exec
	s_mov_b64 exec, s[0:1]
	v_cvt_pk_bf16_f32 v228, v232, v233
	v_cvt_pk_bf16_f32 v229, v234, v235
	v_cvt_pk_bf16_f32 v230, v236, v237
	v_cvt_pk_bf16_f32 v231, v238, v239
	s_mov_b64 exec, s[4:5]
	v_cvt_pk_bf16_f32 v158, v240, v241
	v_cvt_pk_bf16_f32 v159, v242, v243
	v_cvt_pk_bf16_f32 v160, v244, v245
	v_cvt_pk_bf16_f32 v161, v246, v247
	v_cvt_pk_bf16_f32 v176, v248, v249
	v_cvt_pk_bf16_f32 v177, v250, v251
	v_cvt_pk_bf16_f32 v178, v66, v67
	v_cvt_pk_bf16_f32 v179, v68, v69
	s_nop 1
	v_mfma_f32_32x32x16_bf16 v[16:31], v[228:231], v[158:161], v[16:31]
	v_mfma_f32_32x32x16_bf16 v[0:15], v[228:231], v[176:179], v[0:15]
	v_add_u32_e32 v64, 240, v92
	v_lshlrev_b32_e32 v183, 2, v64
	v_lshlrev_b32_e32 v64, 8, v64
	v_lshl_add_u64 v[180:181], v[64:65], 0, v[36:37]
	v_mov_b32_e32 v228, 0
	v_mov_b32_e32 v229, 0
	v_mov_b32_e32 v230, 0
	v_mov_b32_e32 v231, 0
	v_add_u32_e32 v182, 3, v93
	v_cmp_gt_i32_e64 s[40:41], s80, v182
	v_add_u32_e32 v182, s44, v182
	v_mul_u32_u24_e32 v182, s66, v182
	v_add_u32_e32 v64, 48, v46
	v_lshl_add_u32 v182, v64, 1, v182
	s_and_b64 s[40:41], s[40:41], s[38:39]
	s_mov_b64 s[4:5], exec
	s_mov_b64 exec, s[40:41]
	global_load_dwordx4 v[228:231], v182, s[34:35]
	s_mov_b64 exec, s[0:1]
	global_load_dwordx4 v[232:235], v183, s[30:31]
	global_load_dwordx4 v[236:239], v183, s[30:31] offset:16
	s_mov_b64 exec, s[4:5]
	global_load_dword v240, v[180:181], off
	global_load_dword v241, v[180:181], off offset:256
	global_load_dword v242, v[180:181], off offset:512
	global_load_dword v243, v[180:181], off offset:768
	global_load_dword v244, v[180:181], off offset:1024
	global_load_dword v245, v[180:181], off offset:1280
	global_load_dword v246, v[180:181], off offset:1536
	global_load_dword v247, v[180:181], off offset:1792
	global_load_dword v248, v[180:181], off offset:128
	global_load_dword v249, v[180:181], off offset:384
	global_load_dword v250, v[180:181], off offset:640
	global_load_dword v251, v[180:181], off offset:896
	global_load_dword v66, v[180:181], off offset:1152
	global_load_dword v67, v[180:181], off offset:1408
	global_load_dword v68, v[180:181], off offset:1664
	global_load_dword v69, v[180:181], off offset:1920
	s_waitcnt vmcnt(57)
	s_mov_b64 s[4:5], exec
	s_mov_b64 exec, s[0:1]
	v_cvt_pk_bf16_f32 v96, v100, v101
	v_cvt_pk_bf16_f32 v97, v102, v103
	v_cvt_pk_bf16_f32 v98, v104, v105
	v_cvt_pk_bf16_f32 v99, v106, v107
	s_mov_b64 exec, s[4:5]
	v_cvt_pk_bf16_f32 v158, v108, v109
	v_cvt_pk_bf16_f32 v159, v110, v111
	v_cvt_pk_bf16_f32 v160, v112, v113
	v_cvt_pk_bf16_f32 v161, v114, v115
	v_cvt_pk_bf16_f32 v176, v116, v117
	v_cvt_pk_bf16_f32 v177, v118, v119
	v_cvt_pk_bf16_f32 v178, v120, v121
	v_cvt_pk_bf16_f32 v179, v122, v123
	s_nop 1
	v_mfma_f32_32x32x16_bf16 v[16:31], v[96:99], v[158:161], v[16:31]
	v_mfma_f32_32x32x16_bf16 v[0:15], v[96:99], v[176:179], v[0:15]
	s_waitcnt vmcnt(38)
	s_mov_b64 s[4:5], exec
	s_mov_b64 exec, s[0:1]
	v_cvt_pk_bf16_f32 v124, v128, v129
	v_cvt_pk_bf16_f32 v125, v130, v131
	v_cvt_pk_bf16_f32 v126, v132, v133
	v_cvt_pk_bf16_f32 v127, v134, v135
	s_mov_b64 exec, s[4:5]
	v_cvt_pk_bf16_f32 v158, v136, v137
	v_cvt_pk_bf16_f32 v159, v138, v139
	v_cvt_pk_bf16_f32 v160, v140, v141
	v_cvt_pk_bf16_f32 v161, v142, v143
	v_cvt_pk_bf16_f32 v176, v150, v151
	v_cvt_pk_bf16_f32 v177, v152, v153
	v_cvt_pk_bf16_f32 v178, v154, v155
	v_cvt_pk_bf16_f32 v179, v156, v157
	s_nop 1
	v_mfma_f32_32x32x16_bf16 v[16:31], v[124:127], v[158:161], v[16:31]
	v_mfma_f32_32x32x16_bf16 v[0:15], v[124:127], v[176:179], v[0:15]
	s_waitcnt vmcnt(19)
	s_mov_b64 s[4:5], exec
	s_mov_b64 exec, s[0:1]
	v_cvt_pk_bf16_f32 v200, v204, v205
	v_cvt_pk_bf16_f32 v201, v206, v207
	v_cvt_pk_bf16_f32 v202, v208, v209
	v_cvt_pk_bf16_f32 v203, v210, v211
	s_mov_b64 exec, s[4:5]
	v_cvt_pk_bf16_f32 v158, v212, v213
	v_cvt_pk_bf16_f32 v159, v214, v215
	v_cvt_pk_bf16_f32 v160, v216, v217
	v_cvt_pk_bf16_f32 v161, v218, v219
	v_cvt_pk_bf16_f32 v176, v220, v221
	v_cvt_pk_bf16_f32 v177, v222, v223
	v_cvt_pk_bf16_f32 v178, v224, v225
	v_cvt_pk_bf16_f32 v179, v226, v227
	s_nop 1
	v_mfma_f32_32x32x16_bf16 v[16:31], v[200:203], v[158:161], v[16:31]
	v_mfma_f32_32x32x16_bf16 v[0:15], v[200:203], v[176:179], v[0:15]
	s_waitcnt vmcnt(0)
	s_mov_b64 s[4:5], exec
	s_mov_b64 exec, s[0:1]
	v_cvt_pk_bf16_f32 v228, v232, v233
	v_cvt_pk_bf16_f32 v229, v234, v235
	v_cvt_pk_bf16_f32 v230, v236, v237
	v_cvt_pk_bf16_f32 v231, v238, v239
	s_mov_b64 exec, s[4:5]
	v_cvt_pk_bf16_f32 v158, v240, v241
	v_cvt_pk_bf16_f32 v159, v242, v243
	v_cvt_pk_bf16_f32 v160, v244, v245
	v_cvt_pk_bf16_f32 v161, v246, v247
	v_cvt_pk_bf16_f32 v176, v248, v249
	v_cvt_pk_bf16_f32 v177, v250, v251
	v_cvt_pk_bf16_f32 v178, v66, v67
	v_cvt_pk_bf16_f32 v179, v68, v69
	s_nop 1
	v_mfma_f32_32x32x16_bf16 v[16:31], v[228:231], v[158:161], v[16:31]
	v_mfma_f32_32x32x16_bf16 v[0:15], v[228:231], v[176:179], v[0:15]
	s_branch .LBB0_516
